# sample-sequence SSD items assigned statically by workgroup id (no claim atomics) + ssd_scan chunk loads batched
# baseline (speedup 1.0000x reference)
.LBB0_923:
	v_readlane_b32 s4, v255, 23
	s_lshl_b32 s28, s4, 4
	s_lshl_b64 s[2:3], s[28:29], 2
	s_waitcnt lgkmcnt(0)
	s_add_u32 s2, s14, s2
	s_addc_u32 s3, s15, s3
	s_add_u32 s6, s2, 0x445e0
	s_addc_u32 s7, s3, 0
	s_lshl_b32 s30, s4, 3
	v_add_u32_e32 v19, s90, v134
	s_add_u32 s31, s14, 0xdea1a00
	v_ashrrev_i32_e32 v0, 3, v19
	s_addc_u32 s37, s15, 0
	v_ashrrev_i32_e32 v1, 31, v0
	s_add_u32 s8, s14, 0xdea0a00
	v_readlane_b32 s5, v255, 24
	v_and_b32_e32 v2, 7, v134
	v_lshlrev_b64 v[16:17], 9, v[0:1]
	v_lshl_add_u32 v36, v0, 2, 0
	v_lshl_add_u32 v3, v19, 2, 0
	s_addc_u32 s9, s15, 0
	v_lshl_add_u64 v[0:1], v[0:1], 2, s[14:15]
	s_mov_b64 s[2:3], 0x18120200
	s_add_i32 s70, 0, 0x1000
	v_cmp_eq_u32_e64 s[46:47], 0, v19
	v_lshlrev_b32_e32 v18, 4, v2
	v_cmp_eq_u32_e64 s[48:49], 0, v2
	s_lshl_b64 s[22:23], s[4:5], 12
	v_lshl_add_u64 v[20:21], v[0:1], 0, s[2:3]
	v_lshl_add_u32 v37, v2, 6, s70
	v_add_u32_e32 v38, 0x5000, v3
	s_mov_b32 s99, s86
	s_branch .LBB0_926

.LBB0_926:
	s_waitcnt vmcnt(0)
	s_barrier
	s_mov_b32 s2, s99
	s_add_i32 s99, s99, s85
	s_mov_b64 s[4:5], -1
	s_waitcnt lgkmcnt(0)
	s_cmpk_gt_i32 s2, 0xff
	s_cbranch_scc1 .LBB0_925
	s_add_i32 s3, s2, 64
	s_ashr_i32 s4, s3, 3
	s_and_b32 s28, s2, 7
	s_cmp_lt_i32 s4, 8
	s_load_dwordx4 s[52:55], s[10:11], 0x68
	s_load_dwordx2 s[2:3], s[10:11], 0x78
	s_cselect_b64 s[14:15], -1, 0
	s_cmp_gt_i32 s4, 7
	s_cselect_b64 s[24:25], -1, 0
	s_or_b32 s26, s28, s30
	s_mov_b32 s27, s29
	s_add_i32 s50, s4, -8
	s_lshl_b64 s[26:27], s[26:27], 2
	s_waitcnt lgkmcnt(0)
	s_add_u32 s38, s54, s26
	s_addc_u32 s39, s55, s27
	global_load_dword v24, v96, s[38:39]
	s_add_u32 s38, s52, s26
	s_addc_u32 s39, s53, s27
	s_add_u32 s2, s2, s26
	s_addc_u32 s3, s3, s27
	global_load_dword v39, v96, s[38:39]
	global_load_dword v40, v96, s[2:3]
	s_and_b64 vcc, exec, s[24:25]
	v_lshlrev_b32_e32 v22, 2, v18
	s_cbranch_vccz .LBB0_933
	s_load_dwordx2 s[2:3], s[10:11], 0x30
	s_mov_b32 s51, s29
	s_lshl_b64 s[26:27], s[50:51], 3
	s_add_u32 s5, s26, s18
	s_addc_u32 s27, s27, s19
	s_or_b32 s26, s5, s28
	s_lshl_b64 s[26:27], s[26:27], 15
	s_waitcnt lgkmcnt(0)
	s_add_u32 s2, s2, s26
	s_addc_u32 s3, s3, s27
	v_lshl_add_u64 v[0:1], s[2:3], 0, v[16:17]
	v_mov_b32_e32 v23, v96
	v_lshl_add_u64 v[0:1], v[0:1], 0, v[22:23]
	global_load_dwordx4 v[4:7], v[0:1], off
	global_load_dwordx4 v[8:11], v[0:1], off offset:16
	global_load_dwordx4 v[12:15], v[0:1], off offset:32
	s_nop 0
	global_load_dwordx4 v[0:3], v[0:1], off offset:48
	s_mov_b64 s[44:45], s[50:51]
	s_mov_b64 s[26:27], s[28:29]
	s_cbranch_execz .LBB0_934
	s_branch .LBB0_935
